# phase 1 unit order: column panels (8/8/6 tiles) so that an XCD's 32 consecutive units form a ~4x8 tile block
# speedup vs baseline: 1.0061x; 1.0007x over previous
; template <int EPI>
; __device__ __forceinline__ void gemm_phase(const Params& p, const u16* __restrict__ A, int lda, const u16* __restrict__ BT, int ldb,
;                            int K, int N, u16* __restrict__ outb, int ldo, int resid_in, int boff) {
;     ...
;   const int NT = N / 128;
;   const int tiles = (MT / 256) * NT;
;   const int KTALL = K / 64;
;   float* part = (float*)(p.ws + O_PART);
;   int bstart = (int)blockIdx.x - boff;
;   if (bstart < 0) bstart += gridDim.x;
;   const size_t a64 = (size_t)64 * lda, b64 = (size_t)64 * ldb;
;   const int G = gridDim.x;
;   int t_full = tiles, split = 1;
;   if (EPI == EPI_RES) {
;     const int tail = tiles % G;
;     if (tail > 0 && (G % tail) == 0 && (KTALL % (G / tail)) == 0) { t_full = tiles - tail; const int smax = (KTALL >= 64) ? 8 : 4; split = (G / tail) > smax ? smax : (G / tail); }
;   }
;   const int units = t_full + (tiles - t_full) * split;
.Lgm_par1:
	s_add_u32 s16, s96, 0x2f08100
	s_addc_u32 s17, s97, 0
	s_add_u32 s20, s96, 0x0
	s_addc_u32 s21, s97, 0
	s_add_u32 s22, s96, 0x7108100
	s_addc_u32 s23, s97, 0
	s_movk_i32 s24, 0x1600
	s_mov_b32 s25, 22
	s_mov_b32 s26, 0xba2e8bb
	s_mov_b32 s27, 5
	s_movk_i32 s28, 0x5ac
	s_movk_i32 s29, 0x500
	s_mov_b32 s30, 0
	s_movk_i32 s38, 0x5ac
	s_mov_b32 s39, 16
	s_mov_b32 s44, 0
	s_mov_b32 s45, 11
	s_mov_b32 s46, 11
	s_branch .Lgm_common

; template <int EPI>
; __device__ __forceinline__ void gemm_phase(const Params& p, const u16* __restrict__ A, int lda, const u16* __restrict__ BT, int ldb,
;                            int K, int N, u16* __restrict__ outb, int ldo, int resid_in, int boff) {
;     ...
;   for (int un = bstart; un < units; un += G) {
;     int tl = un, kbeg = 0, KT = KTALL;
;     bool part_unit = false;
;     if (un >= t_full) { const int v = un - t_full; tl = t_full + v / split; KT = KTALL / split; kbeg = (v % split) * KT; part_unit = true; }
;     int mt = tl / NT, nt = tl % NT;
;     if (EPI == EPI_RES && NT == 8 && G == 256 && !part_unit) {
;       const int rr = tl >> 8, bb = tl & 255;
;       const int xx = bb & 7, jj = bb >> 3;
;       mt = rr * 32 + xx * 4 + (jj >> 3);
;       nt = jj & 7;
;     } else if ((EPI == EPI_FF1 || EPI == EPI_SCALE) && G == 256 && (NT == 32 || NT == 16) && tl < (tiles & ~255)) {
;       const int rr = tl >> 8, bb = tl & 255;
;       const int xx = bb & 7, jj = bb >> 3;
;       if (NT == 32) { mt = rr * 8 + (xx >> 2) * 4 + (jj >> 3); nt = (xx & 3) * 8 + (jj & 7); }
;       else { mt = rr * 16 + (xx >> 1) * 4 + (jj >> 3); nt = (xx & 1) * 8 + (jj & 7); }
;     }
.Lgc_unit:
	s_cmp_ge_u32 s5, s38
	s_cbranch_scc1 .Lgm_exit
	s_mov_b32 s47, 0
	s_cmp_ge_u32 s5, s28
	s_cbranch_scc1 .Lgm_split_c
	s_mov_b32 s8, 0
	s_mov_b32 s9, s39
	s_mov_b32 s10, 0
	s_cmp_eq_u32 s27, 0
	s_cbranch_scc1 .Lgm_plain_c
	s_cmp_ge_u32 s5, s29
	s_cbranch_scc1 .Lgm_plain_c
	s_cmp_ge_u32 s27, 4
	s_cbranch_scc0 .Lgm_mapped_c
	s_and_b32 s36, s5, 0xffffff00
	s_and_b32 s37, s5, 7
	s_lshl_b32 s37, s37, 5
	s_or_b32 s36, s36, s37
	s_bfe_u32 s37, s5, 0x50003
	s_or_b32 s36, s36, s37
	s_cmp_eq_u32 s27, 5
	s_cbranch_scc1 .Lgm_panel_c
	s_branch .Lgm_plain2_c

; template <int EPI>
; __device__ __forceinline__ void gemm_phase(const Params& p, const u16* __restrict__ A, int lda, const u16* __restrict__ BT, int ldb,
;                            int K, int N, u16* __restrict__ outb, int ldo, int resid_in, int boff) {
;     ...
;   for (int un = bstart; un < units; un += G) {
;     int tl = un, kbeg = 0, KT = KTALL;
;     bool part_unit = false;
;     if (un >= t_full) { const int v = un - t_full; tl = t_full + v / split; KT = KTALL / split; kbeg = (v % split) * KT; part_unit = true; }
;     int mt = tl / NT, nt = tl % NT;
;     if (EPI == EPI_RES && NT == 8 && G == 256 && !part_unit) {
;       const int rr = tl >> 8, bb = tl & 255;
;       const int xx = bb & 7, jj = bb >> 3;
;       mt = rr * 32 + xx * 4 + (jj >> 3);
;       nt = jj & 7;
;     } else if ((EPI == EPI_FF1 || EPI == EPI_SCALE) && G == 256 && (NT == 32 || NT == 16) && tl < (tiles & ~255)) {
;       const int rr = tl >> 8, bb = tl & 255;
;       const int xx = bb & 7, jj = bb >> 3;
;       if (NT == 32) { mt = rr * 8 + (xx >> 2) * 4 + (jj >> 3); nt = (xx & 3) * 8 + (jj & 7); }
;       else { mt = rr * 16 + (xx >> 1) * 4 + (jj >> 3); nt = (xx & 1) * 8 + (jj & 7); }
;     }
.Lgm_plain_c:
	s_mov_b32 s36, s5
	s_cmp_eq_u32 s27, 5
	s_cbranch_scc0 .Lgm_nopanel_c
.Lgm_panel_c:
	s_cmp_ge_u32 s36, 1056
	s_cbranch_scc1 .Lgm_panel2_c
	s_mov_b32 s7, 0
	s_cmp_ge_u32 s36, 528
	s_cbranch_scc0 .Lgm_panel01_c
	s_sub_u32 s36, s36, 528
	s_mov_b32 s7, 8
.Lgm_panel01_c:
	s_lshr_b32 s6, s36, 3
	s_and_b32 s36, s36, 7
	s_add_u32 s7, s7, s36
	s_branch .Lgm_dec_done_c
.Lgm_panel2_c:
	s_sub_u32 s36, s36, 1056
	s_mul_hi_u32 s6, s36, 0x2aaaaaab
	s_mul_i32 s7, s6, 6
	s_sub_u32 s7, s36, s7
	s_add_u32 s7, s7, 16
	s_branch .Lgm_dec_done_c
.Lgm_nopanel_c:
	s_cmp_lg_u32 s30, 5
	s_cbranch_scc1 .Lgm_plain2_c
	s_cmp_lt_u32 s5, 244
	s_cbranch_scc1 .Lgm_plain2_c
	s_add_u32 s36, s5, 140
	s_cmp_lt_u32 s5, 256
	s_cbranch_scc1 .Lgm_plain2_c
	s_mov_b32 s36, s5
	s_cmp_lt_u32 s5, 384
	s_cbranch_scc1 .Lgm_plain2_c
	s_sub_u32 s36, s5, 140

; template <int EPI>
; __device__ __forceinline__ void gemm_phase(const Params& p, const u16* __restrict__ A, int lda, const u16* __restrict__ BT, int ldb,
;                            int K, int N, u16* __restrict__ outb, int ldo, int resid_in, int boff) {
;     ...
;   for (int un = bstart; un < units; un += G) {
;     int tl = un, kbeg = 0, KT = KTALL;
;     bool part_unit = false;
;     if (un >= t_full) { const int v = un - t_full; tl = t_full + v / split; KT = KTALL / split; kbeg = (v % split) * KT; part_unit = true; }
;     int mt = tl / NT, nt = tl % NT;
;     if (EPI == EPI_RES && NT == 8 && G == 256 && !part_unit) {
;       const int rr = tl >> 8, bb = tl & 255;
;       const int xx = bb & 7, jj = bb >> 3;
;       mt = rr * 32 + xx * 4 + (jj >> 3);
;       nt = jj & 7;
;     } else if ((EPI == EPI_FF1 || EPI == EPI_SCALE) && G == 256 && (NT == 32 || NT == 16) && tl < (tiles & ~255)) {
;       const int rr = tl >> 8, bb = tl & 255;
;       const int xx = bb & 7, jj = bb >> 3;
;       if (NT == 32) { mt = rr * 8 + (xx >> 2) * 4 + (jj >> 3); nt = (xx & 3) * 8 + (jj & 7); }
;       else { mt = rr * 16 + (xx >> 1) * 4 + (jj >> 3); nt = (xx & 1) * 8 + (jj & 7); }
;     }
.Lgp_cnt_done:
	s_mov_b32 s11, 0
	s_mov_b32 s18, 0
	s_cmp_ge_u32 s5, s38
	s_cbranch_scc1 .Lgp_su_done_p0
	s_mov_b32 s47, 0
	s_cmp_ge_u32 s5, s28
	s_cbranch_scc1 .Lgm_split_p0
	s_mov_b32 s8, 0
	s_mov_b32 s9, s39
	s_mov_b32 s10, 0
	s_cmp_eq_u32 s27, 0
	s_cbranch_scc1 .Lgm_plain_p0
	s_cmp_ge_u32 s5, s29
	s_cbranch_scc1 .Lgm_plain_p0
	s_cmp_ge_u32 s27, 4
	s_cbranch_scc0 .Lgm_mapped_p0
	s_and_b32 s36, s5, 0xffffff00
	s_and_b32 s37, s5, 7
	s_lshl_b32 s37, s37, 5
	s_or_b32 s36, s36, s37
	s_bfe_u32 s37, s5, 0x50003
	s_or_b32 s36, s36, s37
	s_cmp_eq_u32 s27, 5
	s_cbranch_scc1 .Lgm_panel_p0
	s_branch .Lgm_plain2_p0

; template <int EPI>
; __device__ __forceinline__ void gemm_phase(const Params& p, const u16* __restrict__ A, int lda, const u16* __restrict__ BT, int ldb,
;                            int K, int N, u16* __restrict__ outb, int ldo, int resid_in, int boff) {
;     ...
;   for (int un = bstart; un < units; un += G) {
;     int tl = un, kbeg = 0, KT = KTALL;
;     bool part_unit = false;
;     if (un >= t_full) { const int v = un - t_full; tl = t_full + v / split; KT = KTALL / split; kbeg = (v % split) * KT; part_unit = true; }
;     int mt = tl / NT, nt = tl % NT;
;     if (EPI == EPI_RES && NT == 8 && G == 256 && !part_unit) {
;       const int rr = tl >> 8, bb = tl & 255;
;       const int xx = bb & 7, jj = bb >> 3;
;       mt = rr * 32 + xx * 4 + (jj >> 3);
;       nt = jj & 7;
;     } else if ((EPI == EPI_FF1 || EPI == EPI_SCALE) && G == 256 && (NT == 32 || NT == 16) && tl < (tiles & ~255)) {
;       const int rr = tl >> 8, bb = tl & 255;
;       const int xx = bb & 7, jj = bb >> 3;
;       if (NT == 32) { mt = rr * 8 + (xx >> 2) * 4 + (jj >> 3); nt = (xx & 3) * 8 + (jj & 7); }
;       else { mt = rr * 16 + (xx >> 1) * 4 + (jj >> 3); nt = (xx & 1) * 8 + (jj & 7); }
;     }
;     const int m0 = mt * 256, n0 = nt * 128;
;     const u16* gA = A + (size_t)(m0 + lrow) * lda + lch * 8 + (size_t)kbeg * 64;
;     const u16* gB = BT + (size_t)(n0 + lrow) * ldb + lch * 8 + (size_t)kbeg * 64;
;     uint4 xa0, xa1, xa2, xa3, xb0, xb1;
;     uint4 ya0, ya1, ya2, ya3, yb0, yb1;
.Lgp_is_nop_pa:
	s_add_u32 m0, s31, s32
	s_nop 0
	global_load_lds_dwordx4 v130, s[0:1]
	s_add_u32 m0, m0, 0x400
	s_nop 0
	global_load_lds_dwordx4 v131, s[0:1]
	s_add_u32 m0, m0, 0x400
	s_nop 0
	global_load_lds_dwordx4 v132, s[0:1]
	s_add_u32 m0, m0, 0x400
	s_nop 0
	global_load_lds_dwordx4 v133, s[0:1]
	s_add_u32 m0, m0, 0x400
	s_nop 0
	global_load_lds_dwordx4 v134, s[0:1]
	s_add_u32 m0, m0, 0x400
	s_nop 0
	global_load_lds_dwordx4 v135, s[0:1]
	s_add_u32 m0, m0, 0x400
	s_nop 0
	global_load_lds_dwordx4 v136, s[0:1]
	s_add_u32 m0, m0, 0x400
	s_nop 0
	global_load_lds_dwordx4 v137, s[0:1]
	s_add_u32 m0, s31, s34
	s_nop 0
	global_load_lds_dwordx4 v138, s[2:3]
	s_add_u32 m0, m0, 0x400
	s_nop 0
	global_load_lds_dwordx4 v139, s[2:3]
	s_add_u32 m0, m0, 0x400
	s_nop 0
	global_load_lds_dwordx4 v140, s[2:3]
	s_add_u32 m0, m0, 0x400
	s_nop 0
	global_load_lds_dwordx4 v141, s[2:3]
	s_add_u32 s0, s0, 0x80
	s_addc_u32 s1, s1, 0
	s_add_u32 s2, s2, 0x80
	s_addc_u32 s3, s3, 0
	s_add_u32 s31, s31, 0xc000
	s_cmp_eq_u32 s31, 0x24000
	s_cselect_b32 s31, 0, s31
	s_sub_u32 s18, s18, 1
	s_cmp_lg_u32 s18, 0
	s_cbranch_scc1 .Lgp_is_done_pa
	s_add_u32 s5, s5, s42
	s_mov_b32 s13, s10
	s_mov_b32 s11, 0
	s_mov_b32 s18, 0
	s_cmp_ge_u32 s5, s38
	s_cbranch_scc1 .Lgp_su_done_pau
	s_mov_b32 s47, 0
	s_cmp_ge_u32 s5, s28
	s_cbranch_scc1 .Lgm_split_pau
	s_mov_b32 s8, 0
	s_mov_b32 s9, s39
	s_mov_b32 s10, 0
	s_cmp_eq_u32 s27, 0
	s_cbranch_scc1 .Lgm_plain_pau
	s_cmp_ge_u32 s5, s29
	s_cbranch_scc1 .Lgm_plain_pau
	s_cmp_ge_u32 s27, 4
	s_cbranch_scc0 .Lgm_mapped_pau
	s_and_b32 s36, s5, 0xffffff00
	s_and_b32 s37, s5, 7
	s_lshl_b32 s37, s37, 5
	s_or_b32 s36, s36, s37
	s_bfe_u32 s37, s5, 0x50003
	s_or_b32 s36, s36, s37
	s_cmp_eq_u32 s27, 5
	s_cbranch_scc1 .Lgm_panel_pau
	s_branch .Lgm_plain2_pau
